# last grid barrier split: arrive after ff2, R4 handles its context rows first and waits once before the first latent row
# speedup vs baseline: 1.0127x; 1.0076x over previous
.LBB0_939:
	s_mov_b32 s21, 0
	v_readlane_b32 s0, v254, 39
	v_readlane_b32 s1, v254, 40
	s_cmp_gt_i32 s1, 12
	s_cselect_b64 s[0:1], -1, 0
	s_and_b64 s[2:3], s[6:7], s[0:1]
	s_andn2_b64 vcc, exec, s[2:3]
	s_cbranch_vccnz .LBB0_993
	s_waitcnt vmcnt(0)
	s_barrier
	s_mov_b32 s21, 1
	s_mov_b64 s[4:5], exec
	v_readlane_b32 s6, v254, 2
	v_readlane_b32 s7, v254, 3
	s_nop 1
	s_and_b64 s[6:7], s[4:5], s[6:7]
	s_mov_b64 exec, s[6:7]
	s_cbranch_execz .Lr4_arrive_join
	s_getreg_b32 s8, hwreg(HW_REG_XCC_ID, 0, 4)
	v_mov_b32_e32 v1, 0x23fc0
	ds_read_b64 v[2:3], v1
	s_lshl_b32 s8, s8, 6
	s_add_u32 s10, s62, 0x408000
	s_addc_u32 s11, s63, 0
	v_mov_b32_e32 v4, s8
	v_mov_b32_e32 v5, 1
	global_atomic_add v6, v4, v5, s[10:11] sc0
	s_waitcnt vmcnt(0) lgkmcnt(0)
	v_add_u32_e32 v6, 1, v6
	v_cmp_eq_u32_e32 vcc, v6, v2
	s_cbranch_vccz .Lr4_arrive_join
	buffer_wbl2 sc1
	s_waitcnt vmcnt(0)
	v_mov_b32_e32 v4, 0x400
	global_atomic_add v4, v5, s[10:11]
.Lr4_arrive_join:
	s_mov_b64 exec, s[4:5]
.LBB0_993:
	v_readlane_b32 s14, v254, 39
	s_cmp_lt_i32 s14, 13
	s_cselect_b64 s[2:3], -1, 0
	s_and_b64 s[0:1], s[2:3], s[0:1]
	s_cmpk_lt_i32 s44, 0x2000
	s_cselect_b64 s[2:3], -1, 0
	s_and_b64 s[0:1], s[0:1], s[2:3]
	v_readlane_b32 s15, v254, 40
	s_movk_i32 s9, 0x2000
	s_and_b64 vcc, exec, s[0:1]
	s_cbranch_vccz .LBB0_996
	v_mbcnt_lo_u32_b32 v1, -1, 0
	v_mbcnt_hi_u32_b32 v3, -1, v1
	v_and_b32_e32 v1, 64, v3
	v_add_u32_e32 v4, 64, v1
	v_xor_b32_e32 v1, 1, v3
	v_cmp_lt_i32_e32 vcc, v1, v4
	v_xor_b32_e32 v6, 2, v3
	s_lshl_b32 s2, s44, 1
	v_cndmask_b32_e32 v1, v3, v1, vcc
	v_cmp_lt_i32_e32 vcc, v6, v4
	v_lshlrev_b32_e32 v2, 3, v191
	v_mov_b32_e32 v5, 0
	v_cndmask_b32_e32 v6, v3, v6, vcc
	v_lshlrev_b32_e32 v61, 2, v6
	v_xor_b32_e32 v6, 4, v3
	v_cmp_lt_i32_e32 vcc, v6, v4
	v_or_b32_e32 v8, 0x400, v2
	s_ashr_i32 s3, s2, 31
	v_cndmask_b32_e32 v6, v3, v6, vcc
	v_lshlrev_b32_e32 v75, 2, v6
	v_xor_b32_e32 v6, 8, v3
	v_cmp_lt_i32_e32 vcc, v6, v4
	v_or_b32_e32 v10, 0x600, v2
	v_lshlrev_b32_e32 v12, 2, v8
	v_cndmask_b32_e32 v6, v3, v6, vcc
	v_mov_b32_e32 v13, v5
	s_lshl_b64 s[0:1], s[2:3], 12
	v_lshlrev_b32_e32 v77, 2, v6
	v_xor_b32_e32 v6, 16, v3
	v_lshl_add_u64 v[52:53], s[58:59], 0, v[12:13]
	v_lshlrev_b32_e32 v12, 2, v10
	s_add_u32 s0, s62, s0
	v_cmp_lt_i32_e32 vcc, v6, v4
	v_lshl_add_u64 v[54:55], s[58:59], 0, v[12:13]
	v_lshlrev_b32_e32 v12, 4, v191
	s_addc_u32 s1, s63, s1
	v_cndmask_b32_e32 v6, v3, v6, vcc
	v_lshl_add_u64 v[12:13], s[0:1], 0, v[12:13]
	s_mov_b64 s[0:1], 0x10800000
	s_ashr_i32 s49, s48, 31
	v_lshlrev_b32_e32 v94, 2, v6
	v_xor_b32_e32 v6, 32, v3
	v_lshl_add_u64 v[56:57], v[12:13], 0, s[0:1]
	s_lshl_b64 s[4:5], s[48:49], 12
	s_lshl_b64 s[0:1], s[2:3], 13
	v_cmp_lt_i32_e32 vcc, v6, v4
	s_add_u32 s0, s60, s0
	v_lshlrev_b32_e32 v4, 5, v191
	v_cndmask_b32_e32 v3, v3, v6, vcc
	v_or_b32_e32 v6, 0x200, v2
	s_addc_u32 s1, s61, s1
	v_lshlrev_b32_e32 v1, 2, v1
	v_lshlrev_b32_e32 v95, 2, v3
	v_lshl_add_u64 v[50:51], s[58:59], 0, v[4:5]
	v_lshl_add_u64 v[58:59], s[0:1], 0, v[4:5]
	s_lshl_b64 s[6:7], s[48:49], 13
	s_movk_i32 s3, 0x1000
	s_mov_b32 s12, 0x4001000
	v_lshlrev_b32_e32 v96, 2, v2
	v_lshlrev_b32_e32 v97, 2, v6
	v_lshlrev_b32_e32 v98, 2, v8
	v_lshlrev_b32_e32 v99, 2, v10
	s_mov_b32 s8, 0x3a000000
	s_mov_b32 s13, 0x800000
	s_movk_i32 s14, 0x3000
	v_mov_b32_e32 v60, 0x358637bd
	s_mov_b32 s20, 0
.LBB0_995:
	s_cmp_lg_u32 s20, 2
	s_cbranch_scc1 .Lr4_nowait
	s_cmp_eq_u32 s21, 0
	s_cbranch_scc1 .Lr4_nowait
	s_mov_b64 s[22:23], exec
	v_readlane_b32 s24, v254, 2
	v_readlane_b32 s25, v254, 3
	s_nop 1
	s_and_b64 s[24:25], s[22:23], s[24:25]
	s_mov_b64 exec, s[24:25]
	s_cbranch_execz .Lr4_wait_join
	v_mov_b32_e32 v2, 0x23fc4
	ds_read_b32 v3, v2
	s_add_u32 s26, s62, 0x408000
	s_addc_u32 s27, s63, 0
	v_mov_b32_e32 v2, 0x400
	s_mov_b32 s28, 0
.Lr4_spin:
	global_load_dword v4, v2, s[26:27] sc1
	s_waitcnt vmcnt(0) lgkmcnt(0)
	v_cmp_ge_u32_e32 vcc, v4, v3
	s_cbranch_vccnz .Lr4_spin_done
	s_sleep 1
	s_add_u32 s28, s28, 1
	s_cmp_lt_u32 s28, 0x100000
	s_cbranch_scc1 .Lr4_spin
.Lr4_spin_done:
	buffer_inv sc1
	s_waitcnt vmcnt(0)
.Lr4_wait_join:
	s_mov_b64 exec, s[22:23]
	s_barrier
.Lr4_nowait:
	s_add_u32 s20, s20, 1
	v_add_co_u32_e32 v30, vcc, 0x4000000, v56
	global_load_dwordx4 v[22:25], v[56:57], off
	global_load_dwordx4 v[18:21], v[56:57], off offset:1024
	global_load_dwordx4 v[14:17], v[56:57], off offset:2048
	global_load_dwordx4 v[10:13], v[56:57], off offset:3072
	v_addc_co_u32_e32 v31, vcc, 0, v57, vcc
	v_add_co_u32_e32 v32, vcc, s3, v56
	global_load_dwordx4 v[2:5], v[50:51], off offset:16
	global_load_dwordx4 v[6:9], v[50:51], off
	v_addc_co_u32_e32 v33, vcc, 0, v57, vcc
	global_load_dwordx4 v[78:81], v[30:31], off
	global_load_dwordx4 v[42:45], v[30:31], off offset:1024
	global_load_dwordx4 v[34:37], v[30:31], off offset:2048
	global_load_dwordx4 v[26:29], v[30:31], off offset:3072
	global_load_dwordx4 v[82:85], v[32:33], off
	global_load_dwordx4 v[100:103], v[32:33], off offset:1024
	global_load_dwordx4 v[104:107], v[32:33], off offset:2048
	global_load_dwordx4 v[108:111], v[32:33], off offset:3072
	v_add_co_u32_e32 v66, vcc, s12, v56
	v_add_co_u32_e64 v64, s[0:1], s9, v58
	s_nop 0
	v_addc_co_u32_e32 v67, vcc, 0, v57, vcc
	global_load_dwordx4 v[112:115], v[66:67], off
	global_load_dwordx4 v[46:49], v[66:67], off offset:1024
	global_load_dwordx4 v[38:41], v[66:67], off offset:2048
	global_load_dwordx4 v[30:33], v[66:67], off offset:3072
	v_addc_co_u32_e64 v65, s[0:1], 0, v59, s[0:1]
	v_add_co_u32_e64 v62, s[0:1], s14, v58
	s_add_i32 s10, s2, 0xffffe000
	s_nop 0
	v_addc_co_u32_e64 v63, s[0:1], 0, v59, s[0:1]
	s_lshr_b32 s0, s10, 10
	s_add_i32 s0, s0, 1
	s_cmpk_gt_i32 s2, 0x1fff
	s_cselect_b32 s0, s0, 0
	s_mul_hi_u32 s1, s0, 0xc000
	s_mul_i32 s0, s0, 0xc000
	s_add_u32 s0, s62, s0
	s_addc_u32 s1, s63, s1
	s_add_u32 s10, s0, 0xa000
	s_addc_u32 s11, s1, 0
	global_load_dwordx4 v[116:119], v96, s[10:11] offset:16
	global_load_dwordx4 v[120:123], v96, s[10:11]
	s_add_i32 s2, s2, s48
	v_lshl_add_u64 v[56:57], v[56:57], 0, s[4:5]
	s_cmpk_lt_i32 s2, 0x4000
	s_waitcnt vmcnt(0)
	v_and_b32_e32 v125, 0xffff0000, v22
	v_lshlrev_b32_e32 v124, 16, v22
	v_lshlrev_b32_e32 v126, 16, v23
	v_and_b32_e32 v127, 0xffff0000, v23
	v_lshlrev_b32_e32 v70, 16, v16
	v_and_b32_e32 v71, 0xffff0000, v16
	v_lshlrev_b32_e32 v72, 16, v17
	v_and_b32_e32 v73, 0xffff0000, v17
	v_lshlrev_b32_e32 v16, 16, v12
	v_and_b32_e32 v207, 0xffff0000, v82
	v_and_b32_e32 v17, 0xffff0000, v12
	v_mov_b32_e32 v137, v125
	v_lshlrev_b32_e32 v206, 16, v82
	v_lshlrev_b32_e32 v22, 16, v110
	v_and_b32_e32 v23, 0xffff0000, v110
	v_mov_b32_e32 v136, v207
	v_lshlrev_b32_e32 v86, 16, v18
	v_and_b32_e32 v87, 0xffff0000, v18
	v_lshlrev_b32_e32 v88, 16, v19
	v_and_b32_e32 v89, 0xffff0000, v19
	v_lshlrev_b32_e32 v90, 16, v20
	v_and_b32_e32 v91, 0xffff0000, v20
	v_lshlrev_b32_e32 v92, 16, v21
	v_and_b32_e32 v93, 0xffff0000, v21
	v_mov_b32_e32 v135, v124
	v_pk_mul_f32 v[170:171], v[16:17], v[16:17]
	v_lshlrev_b32_e32 v208, 16, v83
	v_lshlrev_b32_e32 v214, 16, v100
	v_and_b32_e32 v215, 0xffff0000, v100
	v_lshlrev_b32_e32 v216, 16, v101
	v_and_b32_e32 v217, 0xffff0000, v101
	v_lshlrev_b32_e32 v218, 16, v102
	v_and_b32_e32 v219, 0xffff0000, v102
	v_lshlrev_b32_e32 v220, 16, v103
	v_and_b32_e32 v221, 0xffff0000, v103
	v_lshlrev_b32_e32 v18, 16, v108
	v_and_b32_e32 v19, 0xffff0000, v108
	v_lshlrev_b32_e32 v20, 16, v109
	v_and_b32_e32 v21, 0xffff0000, v109
	v_lshlrev_b32_e32 v100, 16, v112
	v_and_b32_e32 v101, 0xffff0000, v112
	v_lshlrev_b32_e32 v102, 16, v113
	v_and_b32_e32 v103, 0xffff0000, v113
	v_mov_b32_e32 v134, v206
	v_pk_mul_f32 v[108:109], v[22:23], v[22:23]
	v_pk_mul_f32 v[112:113], v[136:137], v[136:137]
	v_mov_b32_e32 v139, v126
	v_mov_b32_e32 v203, v170
	v_and_b32_e32 v209, 0xffff0000, v83
	v_mov_b32_e32 v138, v208
	v_mov_b32_e32 v202, v108
	v_mov_b32_e32 v170, v109
	v_pk_fma_f32 v[108:109], v[134:135], v[134:135], v[112:113]
	v_lshlrev_b32_e32 v128, 16, v24
	v_mov_b32_e32 v141, v127
	v_lshlrev_b32_e32 v210, 16, v84
	v_mov_b32_e32 v140, v209
	v_pk_fma_f32 v[108:109], v[138:139], v[138:139], v[108:109]
	v_and_b32_e32 v129, 0xffff0000, v24
	v_mov_b32_e32 v143, v128
	v_and_b32_e32 v211, 0xffff0000, v84
	v_mov_b32_e32 v142, v210
	v_pk_fma_f32 v[108:109], v[140:141], v[140:141], v[108:109]
	v_lshlrev_b32_e32 v130, 16, v25
	v_mov_b32_e32 v145, v129
	v_lshlrev_b32_e32 v212, 16, v85
	v_mov_b32_e32 v144, v211
	v_pk_fma_f32 v[108:109], v[142:143], v[142:143], v[108:109]
	v_and_b32_e32 v131, 0xffff0000, v25
	v_mov_b32_e32 v147, v130
	v_and_b32_e32 v213, 0xffff0000, v85
	v_mov_b32_e32 v146, v212
	v_pk_fma_f32 v[108:109], v[144:145], v[144:145], v[108:109]
	v_mov_b32_e32 v133, v131
	v_mov_b32_e32 v132, v213
	v_pk_fma_f32 v[108:109], v[146:147], v[146:147], v[108:109]
	v_mov_b32_e32 v149, v86
	v_mov_b32_e32 v148, v214
	v_pk_fma_f32 v[108:109], v[132:133], v[132:133], v[108:109]
	v_mov_b32_e32 v151, v87
	v_mov_b32_e32 v150, v215
	v_pk_fma_f32 v[108:109], v[148:149], v[148:149], v[108:109]
	v_mov_b32_e32 v153, v88
	v_mov_b32_e32 v152, v216
	v_pk_fma_f32 v[108:109], v[150:151], v[150:151], v[108:109]
	v_mov_b32_e32 v155, v89
	v_mov_b32_e32 v154, v217
	v_pk_fma_f32 v[108:109], v[152:153], v[152:153], v[108:109]
	v_mov_b32_e32 v157, v90
	v_mov_b32_e32 v156, v218
	v_pk_fma_f32 v[108:109], v[154:155], v[154:155], v[108:109]
	v_mov_b32_e32 v159, v91
	v_mov_b32_e32 v158, v219
	v_pk_fma_f32 v[108:109], v[156:157], v[156:157], v[108:109]
	v_mov_b32_e32 v161, v92
	v_mov_b32_e32 v160, v220
	v_pk_fma_f32 v[108:109], v[158:159], v[158:159], v[108:109]
	v_lshlrev_b32_e32 v66, 16, v14
	v_mov_b32_e32 v163, v93
	v_lshlrev_b32_e32 v194, 16, v78
	v_and_b32_e32 v195, 0xffff0000, v78
	v_lshlrev_b32_e32 v78, 16, v104
	v_mov_b32_e32 v162, v221
	v_pk_fma_f32 v[108:109], v[160:161], v[160:161], v[108:109]
	v_and_b32_e32 v67, 0xffff0000, v14
	v_mov_b32_e32 v165, v66
	v_lshlrev_b32_e32 v196, 16, v79
	v_and_b32_e32 v197, 0xffff0000, v79
	v_and_b32_e32 v79, 0xffff0000, v104
	v_mov_b32_e32 v164, v78
	v_pk_fma_f32 v[108:109], v[162:163], v[162:163], v[108:109]
	v_lshlrev_b32_e32 v68, 16, v15
	v_mov_b32_e32 v167, v67
	v_lshlrev_b32_e32 v198, 16, v80
	v_and_b32_e32 v199, 0xffff0000, v80
	v_lshlrev_b32_e32 v80, 16, v105
	v_mov_b32_e32 v166, v79
	v_pk_fma_f32 v[108:109], v[164:165], v[164:165], v[108:109]
	v_and_b32_e32 v69, 0xffff0000, v15
	v_mov_b32_e32 v169, v68
	v_lshlrev_b32_e32 v200, 16, v81
	v_and_b32_e32 v201, 0xffff0000, v81
	v_and_b32_e32 v81, 0xffff0000, v105
	v_mov_b32_e32 v168, v80
	v_pk_fma_f32 v[108:109], v[166:167], v[166:167], v[108:109]
	v_mov_b32_e32 v175, v69
	v_lshlrev_b32_e32 v82, 16, v106
	v_mov_b32_e32 v174, v81
	v_pk_fma_f32 v[108:109], v[168:169], v[168:169], v[108:109]
	v_mov_b32_e32 v177, v70
	v_and_b32_e32 v83, 0xffff0000, v106
	v_mov_b32_e32 v176, v82
	v_pk_fma_f32 v[108:109], v[174:175], v[174:175], v[108:109]
	v_mov_b32_e32 v179, v71
	v_lshlrev_b32_e32 v84, 16, v107
	v_mov_b32_e32 v178, v83
	v_pk_fma_f32 v[108:109], v[176:177], v[176:177], v[108:109]
	v_mov_b32_e32 v181, v72
	v_and_b32_e32 v85, 0xffff0000, v107
	v_mov_b32_e32 v180, v84
	v_pk_fma_f32 v[108:109], v[178:179], v[178:179], v[108:109]
	v_lshlrev_b32_e32 v14, 16, v10
	v_mov_b32_e32 v183, v73
	v_mov_b32_e32 v182, v85
	v_pk_fma_f32 v[108:109], v[180:181], v[180:181], v[108:109]
	v_and_b32_e32 v15, 0xffff0000, v10
	v_mov_b32_e32 v185, v14
	v_mov_b32_e32 v184, v18
	v_pk_fma_f32 v[108:109], v[182:183], v[182:183], v[108:109]
	v_lshlrev_b32_e32 v10, 16, v11
	v_mov_b32_e32 v187, v15
	v_mov_b32_e32 v186, v19
	v_pk_fma_f32 v[108:109], v[184:185], v[184:185], v[108:109]
	v_and_b32_e32 v11, 0xffff0000, v11
	v_mov_b32_e32 v189, v10
	v_mov_b32_e32 v188, v20
	v_pk_fma_f32 v[108:109], v[186:187], v[186:187], v[108:109]
	v_mov_b32_e32 v193, v11
	v_mov_b32_e32 v192, v21
	v_pk_fma_f32 v[108:109], v[188:189], v[188:189], v[108:109]
	v_lshlrev_b32_e32 v12, 16, v13
	v_and_b32_e32 v13, 0xffff0000, v13
	v_lshlrev_b32_e32 v24, 16, v111
	v_and_b32_e32 v25, 0xffff0000, v111
	v_pk_fma_f32 v[108:109], v[192:193], v[192:193], v[108:109]
	v_pk_mul_f32 v[172:173], v[12:13], v[12:13]
	v_pk_mul_f32 v[110:111], v[24:25], v[24:25]
	v_pk_add_f32 v[108:109], v[202:203], v[108:109]
	v_mov_b32_e32 v205, v172
	v_mov_b32_e32 v204, v110
	v_pk_add_f32 v[108:109], v[170:171], v[108:109]
	v_mov_b32_e32 v172, v111
	v_pk_add_f32 v[108:109], v[204:205], v[108:109]
	v_lshlrev_b32_e32 v104, 16, v114
	v_pk_add_f32 v[108:109], v[172:173], v[108:109]
	ds_bpermute_b32 v111, v1, v109
	ds_bpermute_b32 v110, v1, v108
	v_and_b32_e32 v105, 0xffff0000, v114
	v_lshlrev_b32_e32 v106, 16, v115
	v_and_b32_e32 v107, 0xffff0000, v115
	s_waitcnt lgkmcnt(0)
	v_pk_add_f32 v[108:109], v[108:109], v[110:111]
	ds_bpermute_b32 v111, v61, v109
	ds_bpermute_b32 v110, v61, v108
	s_waitcnt lgkmcnt(0)
	v_pk_add_f32 v[108:109], v[108:109], v[110:111]
	ds_bpermute_b32 v111, v75, v109
	ds_bpermute_b32 v110, v75, v108
	s_waitcnt lgkmcnt(0)
	v_pk_add_f32 v[108:109], v[108:109], v[110:111]
	ds_bpermute_b32 v111, v77, v109
	ds_bpermute_b32 v110, v77, v108
	s_waitcnt lgkmcnt(0)
	v_pk_add_f32 v[108:109], v[108:109], v[110:111]
	ds_bpermute_b32 v111, v94, v109
	ds_bpermute_b32 v110, v94, v108
	s_waitcnt lgkmcnt(0)
	v_pk_add_f32 v[108:109], v[108:109], v[110:111]
	ds_bpermute_b32 v111, v95, v109
	ds_bpermute_b32 v110, v95, v108
	s_waitcnt lgkmcnt(0)
	v_pk_add_f32 v[108:109], v[108:109], v[110:111]
	s_nop 0
	v_pk_fma_f32 v[108:109], v[108:109], s[8:9], v[60:61] op_sel_hi:[1,0,0]
	s_nop 0
	v_mul_f32_e32 v74, 0x4b800000, v109
	v_cmp_gt_f32_e64 s[0:1], s13, v109
	v_mul_f32_e32 v76, 0x4b800000, v108
	v_cmp_gt_f32_e32 vcc, s13, v108
	v_cndmask_b32_e64 v74, v109, v74, s[0:1]
	v_rsq_f32_e32 v74, v74
	v_cndmask_b32_e32 v76, v108, v76, vcc
	v_rsq_f32_e32 v108, v76
	v_mul_f32_e32 v76, 0x45800000, v74
	v_cndmask_b32_e64 v76, v74, v76, s[0:1]
	v_mul_f32_e32 v109, 0x45800000, v108
	v_cndmask_b32_e32 v74, v108, v109, vcc
	v_pk_mul_f32 v[108:109], v[76:77], v[124:125] op_sel_hi:[0,1]
	v_pk_mul_f32 v[110:111], v[76:77], v[126:127] op_sel_hi:[0,1]
	v_pk_mul_f32 v[112:113], v[76:77], v[128:129] op_sel_hi:[0,1]
	v_pk_mul_f32 v[114:115], v[76:77], v[130:131] op_sel_hi:[0,1]
	v_pk_mul_f32 v[124:125], v[74:75], v[206:207] op_sel_hi:[0,1]
	v_pk_mul_f32 v[126:127], v[74:75], v[208:209] op_sel_hi:[0,1]
	v_pk_mul_f32 v[128:129], v[74:75], v[210:211] op_sel_hi:[0,1]
	v_pk_mul_f32 v[130:131], v[74:75], v[212:213] op_sel_hi:[0,1]
	v_pk_mul_f32 v[108:109], v[6:7], v[108:109]
	v_pk_mul_f32 v[110:111], v[8:9], v[110:111]
	v_pk_mul_f32 v[112:113], v[2:3], v[112:113]
	v_pk_mul_f32 v[114:115], v[4:5], v[114:115]
	v_pk_mul_f32 v[124:125], v[6:7], v[124:125]
	v_pk_mul_f32 v[126:127], v[8:9], v[126:127]
	v_pk_mul_f32 v[128:129], v[2:3], v[128:129]
	v_pk_mul_f32 v[130:131], v[4:5], v[130:131]
	v_pk_fma_f32 v[2:3], v[120:121], v[108:109], v[194:195]
	v_pk_fma_f32 v[4:5], v[122:123], v[110:111], v[196:197]
	v_pk_fma_f32 v[6:7], v[116:117], v[112:113], v[198:199]
	v_pk_fma_f32 v[8:9], v[118:119], v[114:115], v[200:201]
	v_pk_fma_f32 v[100:101], v[120:121], v[124:125], v[100:101]
	v_pk_fma_f32 v[102:103], v[122:123], v[126:127], v[102:103]
	v_pk_fma_f32 v[104:105], v[116:117], v[128:129], v[104:105]
	v_pk_fma_f32 v[106:107], v[118:119], v[130:131], v[106:107]
	global_store_dwordx4 v[58:59], v[2:5], off nt
	global_store_dwordx4 v[58:59], v[6:9], off offset:16 nt
	global_store_dwordx4 v[62:63], v[100:103], off offset:-4096 nt
	global_store_dwordx4 v[64:65], v[104:107], off offset:16 nt
	global_load_dwordx4 v[2:5], v[50:51], off offset:2048
	s_nop 0
	global_load_dwordx4 v[6:9], v[50:51], off offset:2064
	global_load_dwordx4 v[100:103], v97, s[10:11]
	global_load_dwordx4 v[104:107], v97, s[10:11] offset:16
	v_pk_mul_f32 v[86:87], v[76:77], v[86:87] op_sel_hi:[0,1]
	v_pk_mul_f32 v[88:89], v[76:77], v[88:89] op_sel_hi:[0,1]
	v_lshlrev_b32_e32 v108, 16, v42
	v_and_b32_e32 v109, 0xffff0000, v42
	v_lshlrev_b32_e32 v42, 16, v43
	v_and_b32_e32 v43, 0xffff0000, v43
	v_pk_mul_f32 v[90:91], v[76:77], v[90:91] op_sel_hi:[0,1]
	v_pk_mul_f32 v[92:93], v[76:77], v[92:93] op_sel_hi:[0,1]
	v_pk_mul_f32 v[116:117], v[74:75], v[214:215] op_sel_hi:[0,1]
	v_pk_mul_f32 v[118:119], v[74:75], v[216:217] op_sel_hi:[0,1]
	v_pk_mul_f32 v[120:121], v[74:75], v[218:219] op_sel_hi:[0,1]
	v_pk_mul_f32 v[122:123], v[74:75], v[220:221] op_sel_hi:[0,1]
	v_lshlrev_b32_e32 v110, 16, v44
	v_and_b32_e32 v111, 0xffff0000, v44
	v_lshlrev_b32_e32 v44, 16, v45
	v_and_b32_e32 v45, 0xffff0000, v45
	v_lshlrev_b32_e32 v112, 16, v46
	v_and_b32_e32 v113, 0xffff0000, v46
	v_lshlrev_b32_e32 v46, 16, v47
	v_and_b32_e32 v47, 0xffff0000, v47
	v_lshlrev_b32_e32 v114, 16, v48
	v_and_b32_e32 v115, 0xffff0000, v48
	v_lshlrev_b32_e32 v48, 16, v49
	v_and_b32_e32 v49, 0xffff0000, v49
	v_pk_mul_f32 v[66:67], v[76:77], v[66:67] op_sel_hi:[0,1]
	v_pk_mul_f32 v[68:69], v[76:77], v[68:69] op_sel_hi:[0,1]
	v_pk_mul_f32 v[70:71], v[76:77], v[70:71] op_sel_hi:[0,1]
	v_pk_mul_f32 v[72:73], v[76:77], v[72:73] op_sel_hi:[0,1]
	v_pk_mul_f32 v[78:79], v[74:75], v[78:79] op_sel_hi:[0,1]
	v_pk_mul_f32 v[80:81], v[74:75], v[80:81] op_sel_hi:[0,1]
	v_pk_mul_f32 v[82:83], v[74:75], v[82:83] op_sel_hi:[0,1]
	v_pk_mul_f32 v[84:85], v[74:75], v[84:85] op_sel_hi:[0,1]
	v_pk_mul_f32 v[14:15], v[76:77], v[14:15] op_sel_hi:[0,1]
	v_pk_mul_f32 v[10:11], v[76:77], v[10:11] op_sel_hi:[0,1]
	v_pk_mul_f32 v[16:17], v[76:77], v[16:17] op_sel_hi:[0,1]
	v_pk_mul_f32 v[12:13], v[76:77], v[12:13] op_sel_hi:[0,1]
	v_pk_mul_f32 v[18:19], v[74:75], v[18:19] op_sel_hi:[0,1]
	v_pk_mul_f32 v[20:21], v[74:75], v[20:21] op_sel_hi:[0,1]
	v_pk_mul_f32 v[22:23], v[74:75], v[22:23] op_sel_hi:[0,1]
	v_pk_mul_f32 v[24:25], v[74:75], v[24:25] op_sel_hi:[0,1]
	s_waitcnt vmcnt(3)
	v_pk_mul_f32 v[86:87], v[2:3], v[86:87]
	v_pk_mul_f32 v[88:89], v[4:5], v[88:89]
	s_waitcnt vmcnt(2)
	v_pk_mul_f32 v[90:91], v[6:7], v[90:91]
	v_pk_mul_f32 v[92:93], v[8:9], v[92:93]
	v_pk_mul_f32 v[116:117], v[2:3], v[116:117]
	v_pk_mul_f32 v[118:119], v[4:5], v[118:119]
	v_pk_mul_f32 v[120:121], v[6:7], v[120:121]
	v_pk_mul_f32 v[122:123], v[8:9], v[122:123]
	s_waitcnt vmcnt(1)
	v_pk_fma_f32 v[2:3], v[100:101], v[86:87], v[108:109]
	v_pk_fma_f32 v[4:5], v[102:103], v[88:89], v[42:43]
	s_waitcnt vmcnt(0)
	v_pk_fma_f32 v[6:7], v[104:105], v[90:91], v[110:111]
	v_pk_fma_f32 v[8:9], v[106:107], v[92:93], v[44:45]
	v_pk_fma_f32 v[42:43], v[100:101], v[116:117], v[112:113]
	v_pk_fma_f32 v[44:45], v[102:103], v[118:119], v[46:47]
	v_pk_fma_f32 v[46:47], v[104:105], v[120:121], v[114:115]
	v_pk_fma_f32 v[48:49], v[106:107], v[122:123], v[48:49]
	global_store_dwordx4 v[58:59], v[2:5], off offset:2048 nt
	global_store_dwordx4 v[58:59], v[6:9], off offset:2064 nt
	global_store_dwordx4 v[64:65], v[42:45], off offset:2048 nt
	global_store_dwordx4 v[64:65], v[46:49], off offset:2064 nt
	global_load_dwordx4 v[2:5], v[52:53], off
	s_nop 0
	global_load_dwordx4 v[6:9], v[52:53], off offset:16
	global_load_dwordx4 v[42:45], v98, s[10:11]
	global_load_dwordx4 v[46:49], v98, s[10:11] offset:16
	v_add_co_u32_e32 v64, vcc, s3, v58
	v_lshlrev_b32_e32 v86, 16, v34
	v_and_b32_e32 v87, 0xffff0000, v34
	v_lshlrev_b32_e32 v34, 16, v35
	v_and_b32_e32 v35, 0xffff0000, v35
	v_addc_co_u32_e32 v65, vcc, 0, v59, vcc
	v_lshlrev_b32_e32 v88, 16, v36
	v_and_b32_e32 v89, 0xffff0000, v36
	v_lshlrev_b32_e32 v36, 16, v37
	v_and_b32_e32 v37, 0xffff0000, v37
	v_lshlrev_b32_e32 v90, 16, v38
	v_and_b32_e32 v91, 0xffff0000, v38
	v_lshlrev_b32_e32 v38, 16, v39
	v_and_b32_e32 v39, 0xffff0000, v39
	v_lshlrev_b32_e32 v92, 16, v40
	v_and_b32_e32 v93, 0xffff0000, v40
	v_lshlrev_b32_e32 v40, 16, v41
	v_and_b32_e32 v41, 0xffff0000, v41
	v_lshl_add_u64 v[58:59], v[58:59], 0, s[6:7]
	s_waitcnt vmcnt(3)
	v_pk_mul_f32 v[66:67], v[2:3], v[66:67]
	v_pk_mul_f32 v[68:69], v[4:5], v[68:69]
	s_waitcnt vmcnt(2)
	v_pk_mul_f32 v[70:71], v[6:7], v[70:71]
	v_pk_mul_f32 v[72:73], v[8:9], v[72:73]
	v_pk_mul_f32 v[78:79], v[2:3], v[78:79]
	v_pk_mul_f32 v[80:81], v[4:5], v[80:81]
	v_pk_mul_f32 v[82:83], v[6:7], v[82:83]
	v_pk_mul_f32 v[84:85], v[8:9], v[84:85]
	s_waitcnt vmcnt(1)
	v_pk_fma_f32 v[2:3], v[42:43], v[66:67], v[86:87]
	v_pk_fma_f32 v[4:5], v[44:45], v[68:69], v[34:35]
	s_waitcnt vmcnt(0)
	v_pk_fma_f32 v[6:7], v[46:47], v[70:71], v[88:89]
	v_pk_fma_f32 v[8:9], v[48:49], v[72:73], v[36:37]
	v_pk_fma_f32 v[34:35], v[42:43], v[78:79], v[90:91]
	v_pk_fma_f32 v[36:37], v[44:45], v[80:81], v[38:39]
	v_pk_fma_f32 v[38:39], v[46:47], v[82:83], v[92:93]
	v_pk_fma_f32 v[40:41], v[48:49], v[84:85], v[40:41]
	global_store_dwordx4 v[64:65], v[2:5], off nt
	global_store_dwordx4 v[64:65], v[6:9], off offset:16 nt
	global_store_dwordx4 v[62:63], v[34:37], off nt
	global_store_dwordx4 v[62:63], v[38:41], off offset:16 nt
	global_load_dwordx4 v[2:5], v[54:55], off
	s_nop 0
	global_load_dwordx4 v[6:9], v[54:55], off offset:16
	global_load_dwordx4 v[34:37], v99, s[10:11]
	global_load_dwordx4 v[38:41], v99, s[10:11] offset:16
	v_lshlrev_b32_e32 v42, 16, v26
	v_and_b32_e32 v43, 0xffff0000, v26
	v_lshlrev_b32_e32 v26, 16, v27
	v_and_b32_e32 v27, 0xffff0000, v27
	v_lshlrev_b32_e32 v44, 16, v28
	v_and_b32_e32 v45, 0xffff0000, v28
	v_lshlrev_b32_e32 v28, 16, v29
	v_and_b32_e32 v29, 0xffff0000, v29
	v_lshlrev_b32_e32 v46, 16, v30
	v_and_b32_e32 v47, 0xffff0000, v30
	v_lshlrev_b32_e32 v30, 16, v31
	v_and_b32_e32 v31, 0xffff0000, v31
	v_lshlrev_b32_e32 v48, 16, v32
	v_and_b32_e32 v49, 0xffff0000, v32
	v_lshlrev_b32_e32 v32, 16, v33
	v_and_b32_e32 v33, 0xffff0000, v33
	s_waitcnt vmcnt(3)
	v_pk_mul_f32 v[14:15], v[14:15], v[2:3]
	v_pk_mul_f32 v[10:11], v[10:11], v[4:5]
	s_waitcnt vmcnt(2)
	v_pk_mul_f32 v[16:17], v[16:17], v[6:7]
	v_pk_mul_f32 v[12:13], v[12:13], v[8:9]
	v_pk_mul_f32 v[18:19], v[2:3], v[18:19]
	v_pk_mul_f32 v[20:21], v[4:5], v[20:21]
	v_pk_mul_f32 v[22:23], v[6:7], v[22:23]
	v_pk_mul_f32 v[24:25], v[8:9], v[24:25]
	s_waitcnt vmcnt(1)
	v_pk_fma_f32 v[2:3], v[14:15], v[34:35], v[42:43]
	v_pk_fma_f32 v[4:5], v[10:11], v[36:37], v[26:27]
	s_waitcnt vmcnt(0)
	v_pk_fma_f32 v[6:7], v[16:17], v[38:39], v[44:45]
	v_pk_fma_f32 v[8:9], v[12:13], v[40:41], v[28:29]
	v_pk_fma_f32 v[10:11], v[34:35], v[18:19], v[46:47]
	v_pk_fma_f32 v[12:13], v[36:37], v[20:21], v[30:31]
	v_pk_fma_f32 v[14:15], v[38:39], v[22:23], v[48:49]
	v_pk_fma_f32 v[16:17], v[40:41], v[24:25], v[32:33]
	global_store_dwordx4 v[64:65], v[2:5], off offset:2048 nt
	global_store_dwordx4 v[64:65], v[6:9], off offset:2064 nt
	global_store_dwordx4 v[62:63], v[10:13], off offset:2048 nt
	global_store_dwordx4 v[62:63], v[14:17], off offset:2064 nt
	s_cbranch_scc1 .LBB0_995
